# O6 + one-hop grid barrier release: the globally last XCD leader bumps every XCD generation word directly (other leaders no longer relay)
# speedup vs baseline: 1.0164x; 1.0042x over previous
; __device__ __forceinline__ unsigned xb_ld(unsigned* p)              { return __hip_atomic_load(p, __ATOMIC_RELAXED, __HIP_MEMORY_SCOPE_AGENT); }
; __device__ __forceinline__ unsigned xb_add(unsigned* p, unsigned v) { return __hip_atomic_fetch_add(p, v, __ATOMIC_RELAXED, __HIP_MEMORY_SCOPE_AGENT); }
; #define XB_SPIN(cond, bar) do { unsigned _sp = 0; while (cond) { __builtin_amdgcn_s_sleep(1); \
;     if ((++_sp & 255u) == 0u) { if (xb_ld(&(bar)[XB_TMO])) break; if (_sp > XB_SPIN_CAP) { atomicAdd(&(bar)[XB_TMO], 1u); break; } } } } while (0)
; __device__ __forceinline__ void xcd_barrier(const XcdBarrier& b, int tid) {
;     ...
;         if (old + 1u == (gen + 1u) * nloc) {
;             __builtin_amdgcn_fence(__ATOMIC_RELEASE, "agent");
;             asm volatile("s_waitcnt vmcnt(0)" ::: "memory");
;             const unsigned og = xb_add(&bar[XB_TOP], 1u);
;             const unsigned tg = og / nx;
;             if (og + 1u == (tg + 1u) * nx) xb_add(&bar[XB_TOPGEN], 1u);
;             else XB_SPIN(xb_ld(&bar[XB_TOPGEN]) == tg, bar);
;             __builtin_amdgcn_fence(__ATOMIC_ACQUIRE, "agent");
;             xb_add(&bar[XB_XGEN(b.x)], 1u);
;             asm volatile("s_waitcnt vmcnt(0)" ::: "memory");
.LBB0_91:
	s_or_b64 exec, exec, s[4:5]
	s_and_saveexec_b64 s[4:5], s[8:9]
	s_cbranch_execz .LBB0_93
	v_mov_b32_e32 v2, 1
	global_atomic_add v[0:1], v2, off
	v_mov_b32_e32 v4, 0xfffff000
	v_mov_b32_e32 v5, -1
	v_lshl_add_u64 v[0:1], v[0:1], 0, v[4:5]
	global_atomic_add v[0:1], v2, off offset:-256
	global_atomic_add v[0:1], v2, off
	global_atomic_add v[0:1], v2, off offset:256
	global_atomic_add v[0:1], v2, off offset:512
	global_atomic_add v[0:1], v2, off offset:768
	global_atomic_add v[0:1], v2, off offset:1024
	global_atomic_add v[0:1], v2, off offset:1280
	global_atomic_add v[0:1], v2, off offset:1536
	global_atomic_add v[0:1], v2, off offset:1792
	global_atomic_add v[0:1], v2, off offset:2048
	global_atomic_add v[0:1], v2, off offset:2304
	global_atomic_add v[0:1], v2, off offset:2560
	global_atomic_add v[0:1], v2, off offset:2816
	global_atomic_add v[0:1], v2, off offset:3072
	global_atomic_add v[0:1], v2, off offset:3328
	global_atomic_add v[0:1], v2, off offset:3584
.LBB0_93:
	s_or_b64 exec, exec, s[4:5]
	v_mov_b32_e32 v0, 0x2000
	v_mov_b32_e32 v1, 1
	s_waitcnt vmcnt(0)
	buffer_inv sc1
	s_nop 0
	s_waitcnt vmcnt(0)

; __device__ __forceinline__ unsigned xb_ld(unsigned* p)              { return __hip_atomic_load(p, __ATOMIC_RELAXED, __HIP_MEMORY_SCOPE_AGENT); }
; __device__ __forceinline__ unsigned xb_add(unsigned* p, unsigned v) { return __hip_atomic_fetch_add(p, v, __ATOMIC_RELAXED, __HIP_MEMORY_SCOPE_AGENT); }
; #define XB_SPIN(cond, bar) do { unsigned _sp = 0; while (cond) { __builtin_amdgcn_s_sleep(1); \
;     if ((++_sp & 255u) == 0u) { if (xb_ld(&(bar)[XB_TMO])) break; if (_sp > XB_SPIN_CAP) { atomicAdd(&(bar)[XB_TMO], 1u); break; } } } } while (0)
; __device__ __forceinline__ void xcd_barrier(const XcdBarrier& b, int tid) {
;     ...
;         if (old + 1u == (gen + 1u) * nloc) {
;             __builtin_amdgcn_fence(__ATOMIC_RELEASE, "agent");
;             asm volatile("s_waitcnt vmcnt(0)" ::: "memory");
;             const unsigned og = xb_add(&bar[XB_TOP], 1u);
;             const unsigned tg = og / nx;
;             if (og + 1u == (tg + 1u) * nx) xb_add(&bar[XB_TOPGEN], 1u);
;             else XB_SPIN(xb_ld(&bar[XB_TOPGEN]) == tg, bar);
;             __builtin_amdgcn_fence(__ATOMIC_ACQUIRE, "agent");
;             xb_add(&bar[XB_XGEN(b.x)], 1u);
;             asm volatile("s_waitcnt vmcnt(0)" ::: "memory");
.LBB0_205:
	s_or_b64 exec, exec, s[2:3]
	s_and_saveexec_b64 s[2:3], s[4:5]
	s_cbranch_execz .LBB0_207
	global_atomic_add v[0:1], v239, off
	v_mov_b32_e32 v2, 0xfffff000
	v_mov_b32_e32 v3, -1
	v_lshl_add_u64 v[0:1], v[0:1], 0, v[2:3]
	global_atomic_add v[0:1], v239, off offset:-256
	global_atomic_add v[0:1], v239, off
	global_atomic_add v[0:1], v239, off offset:256
	global_atomic_add v[0:1], v239, off offset:512
	global_atomic_add v[0:1], v239, off offset:768
	global_atomic_add v[0:1], v239, off offset:1024
	global_atomic_add v[0:1], v239, off offset:1280
	global_atomic_add v[0:1], v239, off offset:1536
	global_atomic_add v[0:1], v239, off offset:1792
	global_atomic_add v[0:1], v239, off offset:2048
	global_atomic_add v[0:1], v239, off offset:2304
	global_atomic_add v[0:1], v239, off offset:2560
	global_atomic_add v[0:1], v239, off offset:2816
	global_atomic_add v[0:1], v239, off offset:3072
	global_atomic_add v[0:1], v239, off offset:3328
	global_atomic_add v[0:1], v239, off offset:3584
.LBB0_207:
	s_or_b64 exec, exec, s[2:3]
	v_readlane_b32 s2, v254, 9
	v_readlane_b32 s3, v254, 10
	s_waitcnt vmcnt(0)
	buffer_inv sc1
	s_nop 2
	s_nop 0
	s_waitcnt vmcnt(0)

; __device__ __forceinline__ unsigned xb_ld(unsigned* p)              { return __hip_atomic_load(p, __ATOMIC_RELAXED, __HIP_MEMORY_SCOPE_AGENT); }
; __device__ __forceinline__ unsigned xb_add(unsigned* p, unsigned v) { return __hip_atomic_fetch_add(p, v, __ATOMIC_RELAXED, __HIP_MEMORY_SCOPE_AGENT); }
; #define XB_SPIN(cond, bar) do { unsigned _sp = 0; while (cond) { __builtin_amdgcn_s_sleep(1); \
;     if ((++_sp & 255u) == 0u) { if (xb_ld(&(bar)[XB_TMO])) break; if (_sp > XB_SPIN_CAP) { atomicAdd(&(bar)[XB_TMO], 1u); break; } } } } while (0)
; __device__ __forceinline__ void xcd_barrier(const XcdBarrier& b, int tid) {
;     ...
;         if (old + 1u == (gen + 1u) * nloc) {
;             __builtin_amdgcn_fence(__ATOMIC_RELEASE, "agent");
;             asm volatile("s_waitcnt vmcnt(0)" ::: "memory");
;             const unsigned og = xb_add(&bar[XB_TOP], 1u);
;             const unsigned tg = og / nx;
;             if (og + 1u == (tg + 1u) * nx) xb_add(&bar[XB_TOPGEN], 1u);
;             else XB_SPIN(xb_ld(&bar[XB_TOPGEN]) == tg, bar);
;             __builtin_amdgcn_fence(__ATOMIC_ACQUIRE, "agent");
;             xb_add(&bar[XB_XGEN(b.x)], 1u);
;             asm volatile("s_waitcnt vmcnt(0)" ::: "memory");
.LBB0_1531:
	s_or_b64 exec, exec, s[4:5]
	s_and_saveexec_b64 s[4:5], s[6:7]
	s_cbranch_execz .LBB0_1533
	global_atomic_add v[0:1], v239, off
	v_mov_b32_e32 v2, 0xfffff000
	v_mov_b32_e32 v3, -1
	v_lshl_add_u64 v[0:1], v[0:1], 0, v[2:3]
	global_atomic_add v[0:1], v239, off offset:-256
	global_atomic_add v[0:1], v239, off
	global_atomic_add v[0:1], v239, off offset:256
	global_atomic_add v[0:1], v239, off offset:512
	global_atomic_add v[0:1], v239, off offset:768
	global_atomic_add v[0:1], v239, off offset:1024
	global_atomic_add v[0:1], v239, off offset:1280
	global_atomic_add v[0:1], v239, off offset:1536
	global_atomic_add v[0:1], v239, off offset:1792
	global_atomic_add v[0:1], v239, off offset:2048
	global_atomic_add v[0:1], v239, off offset:2304
	global_atomic_add v[0:1], v239, off offset:2560
	global_atomic_add v[0:1], v239, off offset:2816
	global_atomic_add v[0:1], v239, off offset:3072
	global_atomic_add v[0:1], v239, off offset:3328
	global_atomic_add v[0:1], v239, off offset:3584
.LBB0_1533:
	s_or_b64 exec, exec, s[4:5]
	v_readlane_b32 s0, v254, 9
	v_readlane_b32 s1, v254, 10
	s_waitcnt vmcnt(0)
	buffer_inv sc1
	s_nop 2
	s_nop 0
	s_waitcnt vmcnt(0)

; __device__ __forceinline__ unsigned xb_ld(unsigned* p)              { return __hip_atomic_load(p, __ATOMIC_RELAXED, __HIP_MEMORY_SCOPE_AGENT); }
; __device__ __forceinline__ unsigned xb_add(unsigned* p, unsigned v) { return __hip_atomic_fetch_add(p, v, __ATOMIC_RELAXED, __HIP_MEMORY_SCOPE_AGENT); }
; #define XB_SPIN(cond, bar) do { unsigned _sp = 0; while (cond) { __builtin_amdgcn_s_sleep(1); \
;     if ((++_sp & 255u) == 0u) { if (xb_ld(&(bar)[XB_TMO])) break; if (_sp > XB_SPIN_CAP) { atomicAdd(&(bar)[XB_TMO], 1u); break; } } } } while (0)
; __device__ __forceinline__ void xcd_barrier(const XcdBarrier& b, int tid) {
;     ...
;         if (old + 1u == (gen + 1u) * nloc) {
;             __builtin_amdgcn_fence(__ATOMIC_RELEASE, "agent");
;             asm volatile("s_waitcnt vmcnt(0)" ::: "memory");
;             const unsigned og = xb_add(&bar[XB_TOP], 1u);
;             const unsigned tg = og / nx;
;             if (og + 1u == (tg + 1u) * nx) xb_add(&bar[XB_TOPGEN], 1u);
;             else XB_SPIN(xb_ld(&bar[XB_TOPGEN]) == tg, bar);
;             __builtin_amdgcn_fence(__ATOMIC_ACQUIRE, "agent");
;             xb_add(&bar[XB_XGEN(b.x)], 1u);
;             asm volatile("s_waitcnt vmcnt(0)" ::: "memory");
.LBB0_1855:
	s_or_b64 exec, exec, s[2:3]
	s_and_saveexec_b64 s[2:3], s[4:5]
	s_cbranch_execz .LBB0_1857
	v_mov_b32_e32 v2, 1
	global_atomic_add v[0:1], v2, off
	v_mov_b32_e32 v4, 0xfffff000
	v_mov_b32_e32 v5, -1
	v_lshl_add_u64 v[0:1], v[0:1], 0, v[4:5]
	global_atomic_add v[0:1], v2, off offset:-256
	global_atomic_add v[0:1], v2, off
	global_atomic_add v[0:1], v2, off offset:256
	global_atomic_add v[0:1], v2, off offset:512
	global_atomic_add v[0:1], v2, off offset:768
	global_atomic_add v[0:1], v2, off offset:1024
	global_atomic_add v[0:1], v2, off offset:1280
	global_atomic_add v[0:1], v2, off offset:1536
	global_atomic_add v[0:1], v2, off offset:1792
	global_atomic_add v[0:1], v2, off offset:2048
	global_atomic_add v[0:1], v2, off offset:2304
	global_atomic_add v[0:1], v2, off offset:2560
	global_atomic_add v[0:1], v2, off offset:2816
	global_atomic_add v[0:1], v2, off offset:3072
	global_atomic_add v[0:1], v2, off offset:3328
	global_atomic_add v[0:1], v2, off offset:3584
.LBB0_1857:
	s_or_b64 exec, exec, s[2:3]
	v_readlane_b32 s2, v254, 9
	v_mov_b32_e32 v0, 0
	v_mov_b32_e32 v1, 1
	v_readlane_b32 s3, v254, 10
	s_waitcnt vmcnt(0)
	buffer_inv sc1
	s_nop 2
	s_nop 0
	s_waitcnt vmcnt(0)
